# position lookup for P1 loaded at kernel start instead of after the first grid barrier
# speedup vs baseline: 1.0004x; 1.0004x over previous
; #define LAS __attribute__((address_space(3)))
; __device__ __forceinline__ void tr_load(const TrDesc& d, int lane, TrRegs& t) {
;     const int nblk = d.N / 32, kb = d.item / nblk, nb = d.item - kb * nblk, k0 = 64 * kb, n0 = 32 * nb;
;     const float* src = d.W + (size_t)(k0 + (lane >> 5)) * d.N + n0 + (lane & 31);
; #pragma unroll
;     for (int i = 0; i < 32; ++i) t.v[i] = __builtin_nontemporal_load(src + (size_t)(2 * i) * d.N);
;     const int c = lane & 7;
;     t.g0 = (f32x4){1.f, 1.f, 1.f, 1.f}; t.g1 = t.g0;
;     if (d.gs) { t.g0 = *(const f32x4*)(d.gs + k0 + 8 * c); t.g1 = *(const f32x4*)(d.gs + k0 + 8 * c + 4); }
; }
; __global__ void __launch_bounds__(NWAVES * 64, 2) hymba_fwd(Args a) {
;     ...
;             LAS float* scr = (LAS float*)(lds + wave * 16384);
;     ...
;             constexpr int NITEMS = I_IN;
;     ...
;             TrDesc dc, dn; TrRegs tc, tn;
;             const int NCW = (G - NG) * NWAVES; int it = (bx - NG) * NWAVES + wave;
;             if (it < NITEMS) { EARLY_DESC(dc, it); tr_load(dc, lane, tc); }
;             while (it < NITEMS) {
;                 const int nx = it + NCW; const bool more = nx < NITEMS;
;                 if (more) { EARLY_DESC(dn, nx); tr_load(dn, lane, tn); }
.LBB0_15:
	s_or_b64 exec, exec, s[4:5]
	s_load_dwordx16 s[56:71], s[0:1], 0x0
	s_waitcnt lgkmcnt(0)
	v_and_b32_e32 v251, 0xff, v0
	v_lshl_add_u32 v250, s86, 8, v251
	v_lshlrev_b32_e32 v250, 2, v250
	global_load_dword v252, v250, s[58:59]
	v_mov_b32_e32 v22, v0
	s_add_u32 s12, s94, 0x200000
	s_addc_u32 s13, s95, 0
	v_readfirstlane_b32 s3, v22
	s_ashr_i32 s19, s3, 6
	s_cmp_lt_i32 s2, 64
	s_cselect_b64 s[14:15], -1, 0
	s_cmp_gt_i32 s2, 63
	v_and_b32_e32 v32, 63, v22
	s_cbranch_scc0 .LBB0_19
	s_add_i32 s8, s18, s19
	s_add_i32 s16, s8, 0xfffffe00
	s_cmpk_lt_i32 s16, 0xa00
	s_cselect_b64 s[4:5], -1, 0
	s_cmpk_gt_i32 s16, 0x9ff
	v_lshrrev_b32_e32 v1, 5, v32
	v_and_b32_e32 v10, 31, v22
	s_cbranch_scc1 .LBB0_20
	s_mul_hi_i32 s3, s16, 0x66666667
	s_lshr_b32 s6, s3, 31
	s_ashr_i32 s3, s3, 5
	s_add_i32 s3, s3, s6
	s_mul_i32 s6, s3, 0xffffffb0
	s_add_i32 s7, s6, s16
	s_lshl_b32 s6, s3, 6
	s_lshl_b32 s10, s7, 5
	v_or_b32_e32 v4, s6, v1
	s_movk_i32 s3, 0x2800
	s_waitcnt lgkmcnt(0)
	v_mov_b64_e32 v[2:3], s[62:63]
	v_mad_i64_i32 v[2:3], s[20:21], v4, s3, v[2:3]
	s_ashr_i32 s11, s10, 31
	v_lshl_add_u64 v[2:3], s[10:11], 2, v[2:3]
	v_lshlrev_b32_e32 v4, 2, v10
	v_mov_b32_e32 v5, 0
	v_lshl_add_u64 v[2:3], v[2:3], 0, v[4:5]
	s_movk_i32 s3, 0x5000
	v_add_co_u32_e32 v4, vcc, s3, v2
	s_mov_b32 s3, 0xa000
	s_nop 0
	v_addc_co_u32_e32 v5, vcc, 0, v3, vcc
	v_add_co_u32_e32 v6, vcc, s3, v2
	s_mov_b32 s3, 0xf000
	s_nop 0
	v_addc_co_u32_e32 v7, vcc, 0, v3, vcc
	v_add_co_u32_e32 v8, vcc, s3, v2
	s_mov_b32 s3, 0x14000
	s_nop 0
	v_addc_co_u32_e32 v9, vcc, 0, v3, vcc
	v_add_co_u32_e32 v12, vcc, s3, v2
	s_mov_b32 s3, 0x19000
	s_nop 0
	v_addc_co_u32_e32 v13, vcc, 0, v3, vcc
	v_add_co_u32_e32 v14, vcc, s3, v2
	s_mov_b32 s3, 0x1e000
	s_nop 0
	v_addc_co_u32_e32 v15, vcc, 0, v3, vcc
	v_add_co_u32_e32 v16, vcc, s3, v2
	s_mov_b32 s3, 0x23000
	s_nop 0
	v_addc_co_u32_e32 v17, vcc, 0, v3, vcc
	v_add_co_u32_e32 v24, vcc, s3, v2
	s_mov_b32 s3, 0x28000
	s_nop 0
	v_addc_co_u32_e32 v25, vcc, 0, v3, vcc
	global_load_dword v18, v[2:3], off nt
	global_load_dword v21, v[4:5], off nt
	global_load_dword v20, v[6:7], off nt
	global_load_dword v38, v[8:9], off nt
	global_load_dword v19, v[12:13], off nt
	global_load_dword v31, v[14:15], off nt
	global_load_dword v30, v[16:17], off nt
	global_load_dword v39, v[24:25], off nt
	v_add_co_u32_e32 v4, vcc, s3, v2
	s_mov_b32 s3, 0x2d000
	s_nop 0
	v_addc_co_u32_e32 v5, vcc, 0, v3, vcc
	v_add_co_u32_e32 v6, vcc, s3, v2
	s_mov_b32 s3, 0x32000
	s_nop 0
	v_addc_co_u32_e32 v7, vcc, 0, v3, vcc
	v_add_co_u32_e32 v8, vcc, s3, v2
	s_mov_b32 s3, 0x37000
	s_nop 0
	v_addc_co_u32_e32 v9, vcc, 0, v3, vcc
	v_add_co_u32_e32 v12, vcc, s3, v2
	s_mov_b32 s3, 0x3c000
	s_nop 0
	v_addc_co_u32_e32 v13, vcc, 0, v3, vcc
	v_add_co_u32_e32 v14, vcc, s3, v2
	s_mov_b32 s3, 0x41000
	s_nop 0
	v_addc_co_u32_e32 v15, vcc, 0, v3, vcc
	v_add_co_u32_e32 v16, vcc, s3, v2
	s_mov_b32 s3, 0x46000
	s_nop 0
	v_addc_co_u32_e32 v17, vcc, 0, v3, vcc
	v_add_co_u32_e32 v24, vcc, s3, v2
	s_mov_b32 s3, 0x4b000
	s_nop 0
	v_addc_co_u32_e32 v25, vcc, 0, v3, vcc
	v_add_co_u32_e32 v26, vcc, s3, v2
	s_mov_b32 s3, 0x50000
	s_nop 0
	v_addc_co_u32_e32 v27, vcc, 0, v3, vcc
	global_load_dword v40, v[4:5], off nt
	global_load_dword v43, v[6:7], off nt
	global_load_dword v42, v[8:9], off nt
	global_load_dword v46, v[12:13], off nt
	global_load_dword v41, v[14:15], off nt
	global_load_dword v45, v[16:17], off nt
	global_load_dword v44, v[24:25], off nt
	global_load_dword v47, v[26:27], off nt
	v_add_co_u32_e32 v4, vcc, s3, v2
	s_mov_b32 s3, 0x55000
	s_nop 0
	v_addc_co_u32_e32 v5, vcc, 0, v3, vcc
	v_add_co_u32_e32 v6, vcc, s3, v2
	s_mov_b32 s3, 0x5a000
	s_nop 0
	v_addc_co_u32_e32 v7, vcc, 0, v3, vcc
	v_add_co_u32_e32 v8, vcc, s3, v2
	s_mov_b32 s3, 0x5f000
	s_nop 0
	v_addc_co_u32_e32 v9, vcc, 0, v3, vcc
	v_add_co_u32_e32 v12, vcc, s3, v2
	s_mov_b32 s3, 0x64000
	s_nop 0
	v_addc_co_u32_e32 v13, vcc, 0, v3, vcc
	v_add_co_u32_e32 v14, vcc, s3, v2
	s_mov_b32 s3, 0x69000
	s_nop 0
	v_addc_co_u32_e32 v15, vcc, 0, v3, vcc
	v_add_co_u32_e32 v16, vcc, s3, v2
	s_mov_b32 s3, 0x6e000
	s_nop 0
	v_addc_co_u32_e32 v17, vcc, 0, v3, vcc
	v_add_co_u32_e32 v24, vcc, s3, v2
	s_mov_b32 s3, 0x73000
	s_nop 0
	v_addc_co_u32_e32 v25, vcc, 0, v3, vcc
	v_add_co_u32_e32 v26, vcc, s3, v2
	s_mov_b32 s3, 0x78000
	s_nop 0
	v_addc_co_u32_e32 v27, vcc, 0, v3, vcc
	global_load_dword v55, v[4:5], off nt
	global_load_dword v58, v[6:7], off nt
	global_load_dword v57, v[8:9], off nt
	global_load_dword v61, v[12:13], off nt
	global_load_dword v56, v[14:15], off nt
	global_load_dword v60, v[16:17], off nt
	global_load_dword v59, v[24:25], off nt
	global_load_dword v62, v[26:27], off nt
	v_add_co_u32_e32 v4, vcc, s3, v2
	s_mov_b32 s3, 0x7d000
	s_nop 0
	v_addc_co_u32_e32 v5, vcc, 0, v3, vcc
	v_add_co_u32_e32 v6, vcc, s3, v2
	s_mov_b32 s3, 0x82000
	s_nop 0
	v_addc_co_u32_e32 v7, vcc, 0, v3, vcc
	v_add_co_u32_e32 v8, vcc, s3, v2
	s_mov_b32 s3, 0x87000
	s_nop 0
	v_addc_co_u32_e32 v9, vcc, 0, v3, vcc
	v_add_co_u32_e32 v12, vcc, s3, v2
	s_mov_b32 s3, 0x8c000
	s_nop 0
	v_addc_co_u32_e32 v13, vcc, 0, v3, vcc
	v_add_co_u32_e32 v14, vcc, s3, v2
	s_mov_b32 s3, 0x91000
	s_nop 0
	v_addc_co_u32_e32 v15, vcc, 0, v3, vcc
	v_add_co_u32_e32 v16, vcc, s3, v2
	s_cmp_eq_u64 s[60:61], 0
	s_nop 0
	v_addc_co_u32_e32 v17, vcc, 0, v3, vcc
	v_add_co_u32_e32 v24, vcc, 0x96000, v2
	s_nop 1
	v_addc_co_u32_e32 v25, vcc, 0, v3, vcc
	v_add_co_u32_e32 v2, vcc, 0x9b000, v2
	s_nop 1
	v_addc_co_u32_e32 v3, vcc, 0, v3, vcc
	global_load_dword v70, v[4:5], off nt
	global_load_dword v74, v[6:7], off nt
	global_load_dword v73, v[8:9], off nt
	global_load_dword v77, v[12:13], off nt
	global_load_dword v72, v[14:15], off nt
	global_load_dword v76, v[16:17], off nt
	global_load_dword v75, v[24:25], off nt
	global_load_dword v78, v[2:3], off nt
	s_cbranch_scc1 .LBB0_21
	s_ashr_i32 s7, s6, 31
	s_lshl_b64 s[6:7], s[6:7], 2
	s_add_u32 s6, s60, s6
	v_lshlrev_b32_e32 v2, 5, v32
	s_addc_u32 s7, s61, s7
	v_and_b32_e32 v11, 0xe0, v2
	global_load_dwordx4 v[6:9], v11, s[6:7]
	global_load_dwordx4 v[2:5], v11, s[6:7] offset:16
	s_lshl_b32 s17, s33, 3
	s_andn2_b64 vcc, exec, s[4:5]
	s_add_i32 s3, s17, 0xfffffe00
	s_cbranch_vccz .LBB0_22
	s_branch .LBB0_61

; #define LAS __attribute__((address_space(3)))
; #define LDS_WAIT() asm volatile("s_waitcnt lgkmcnt(0)" ::: "memory")
; __global__ void __launch_bounds__(NWAVES * 64, 2) hymba_fwd(Args a) {
;     ...
;         LAS int* posl = (LAS int*)(lds + LDSCTL_OFF + 1024);
;         if (tid_l < 256) posl[tid_l] = a.pos[team_pm * 256 + tid_l];
;         LDS_WAIT(); __syncthreads();
.LBB0_392:
	s_or_b64 exec, exec, s[0:1]
	s_waitcnt vmcnt(0) lgkmcnt(0)
	v_mov_b32_e32 v2, v0
	s_movk_i32 s0, 0x100
	s_barrier
	s_nop 0
	v_cmp_gt_i32_e32 vcc, s0, v2
	s_and_saveexec_b64 s[0:1], vcc
	s_cbranch_execz .LBB0_394
	v_lshl_add_u32 v6, s86, 8, v2
	v_mov_b32_e32 v4, s58
	v_mov_b32_e32 v5, s59
	v_ashrrev_i32_e32 v7, 31, v6
	v_lshl_add_u64 v[4:5], v[6:7], 2, v[4:5]
	v_mov_b32_e32 v3, v252
	v_lshl_add_u32 v2, v2, 2, 0
	v_add_u32_e32 v2, 0x20400, v2
	s_waitcnt vmcnt(0)
	ds_write_b32 v2, v3
